# dense-GQA attention loop: next-tile LDS-DMA issued after the first K-fragment ds_reads of each step instead of first thing after the barrier
# baseline (speedup 1.0000x reference)
.LBB0_399:
	s_add_i32 s34, s56, 0xfffc0000
	s_add_i32 s30, s55, -1
	s_and_b32 s34, s34, 0xf00000
	s_and_b32 s30, s30, 3
	s_lshl_b32 s78, s34, 1
	s_add_i32 s54, s29, 0
	s_mul_i32 s58, s30, 0x38000
	s_mov_b32 s59, s79
	s_add_i32 s34, s54, s5
	s_add_i32 s35, s34, 0x2000
	s_mov_b32 s30, s27
	s_mov_b32 s27, s72
	s_add_i32 s53, s30, 0
	v_add_u32_e32 v0, s53, v126
	ds_read_b128 v[34:37], v0
	ds_read_b128 v[38:41], v0 offset:2048
	v_lshl_add_u64 v[238:239], v[116:117], 0, s[78:79]
	s_mov_b32 m0, s34
	v_lshl_add_u64 v[238:239], v[238:239], 0, s[58:59]
	global_load_lds_dwordx4 v[238:239], off
	v_lshl_add_u64 v[238:239], v[118:119], 0, s[78:79]
	s_mov_b32 m0, s35
	v_lshl_add_u64 v[238:239], v[238:239], 0, s[58:59]
	global_load_lds_dwordx4 v[238:239], off
	v_exp_f32_e32 v145, v66
	v_exp_f32_e32 v146, v67
	v_exp_f32_e32 v147, v68
	v_exp_f32_e32 v148, v69
	v_exp_f32_e32 v149, v70
	v_exp_f32_e32 v150, v71
	v_exp_f32_e32 v151, v72
	s_waitcnt lgkmcnt(0)
	v_mfma_f32_32x32x16_bf16 v[82:97], v[34:37], v[110:113], v[50:65]
	ds_read_b128 v[34:37], v0 offset:4096
	v_exp_f32_e32 v152, v73
	v_exp_f32_e32 v153, v74
	v_exp_f32_e32 v154, v75
	v_exp_f32_e32 v155, v76
	v_exp_f32_e32 v156, v77
	v_exp_f32_e32 v157, v78
	v_mfma_f32_32x32x16_bf16 v[82:97], v[38:41], v[106:109], v[82:97]
	ds_read_b128 v[38:41], v0 offset:6144
	v_exp_f32_e32 v158, v79
	v_exp_f32_e32 v159, v80
	v_exp_f32_e32 v160, v81
	s_waitcnt lgkmcnt(0)
	v_mfma_f32_32x32x16_bf16 v[82:97], v[34:37], v[102:105], v[82:97]
	v_add_f32_e32 v34, v129, v131
	v_add_f32_e32 v66, v132, v34
	ds_read_b128 v[34:37], v0 offset:512
	ds_read_b128 v[42:45], v0 offset:2560
	ds_read_b128 v[46:49], v0 offset:4608
	v_mfma_f32_32x32x16_bf16 v[82:97], v[38:41], v[98:101], v[82:97]
	ds_read_b128 v[38:41], v0 offset:6656
	v_add_f32_e32 v0, v135, v66
	v_add_f32_e32 v0, v136, v0
	v_add_f32_e32 v0, v139, v0
	v_add_f32_e32 v0, v140, v0
	v_add_f32_e32 v0, v143, v0
	v_add_f32_e32 v0, v130, v0
	s_waitcnt lgkmcnt(0)
	v_mfma_f32_32x32x16_bf16 v[66:81], v[34:37], v[110:113], v[50:65]
	v_add_f32_e32 v0, v133, v0
	v_add_f32_e32 v0, v134, v0
	v_add_f32_e32 v0, v137, v0
	v_add_f32_e32 v0, v138, v0
	v_add_f32_e32 v0, v141, v0
	v_add_f32_e32 v0, v142, v0
	v_add_f32_e32 v0, v144, v0
	v_mfma_f32_32x32x16_bf16 v[66:81], v[42:45], v[106:109], v[66:81]
	v_add_f32_e32 v0, v145, v0
	v_add_f32_e32 v0, v146, v0
	v_add_f32_e32 v0, v147, v0
	v_add_f32_e32 v0, v148, v0
	v_add_f32_e32 v0, v149, v0
	v_add_f32_e32 v0, v150, v0
	v_add_f32_e32 v0, v151, v0
	v_mfma_f32_32x32x16_bf16 v[66:81], v[46:49], v[102:105], v[66:81]
	v_add_f32_e32 v0, v152, v0
	v_add_f32_e32 v0, v153, v0
	v_add_f32_e32 v0, v154, v0
	v_add_f32_e32 v0, v155, v0
	v_add_f32_e32 v0, v156, v0
	v_add_f32_e32 v0, v157, v0
	v_add_f32_e32 v0, v158, v0
	v_mfma_f32_32x32x16_bf16 v[66:81], v[38:41], v[98:101], v[66:81]
	v_cvt_pk_bf16_f32 v34, v129, v131
	v_add_f32_e32 v161, v159, v0
	v_cvt_pk_bf16_f32 v35, v132, v135
	v_cvt_pk_bf16_f32 v36, v136, v139
	v_cvt_pk_bf16_f32 v37, v140, v143
	v_cvt_pk_bf16_f32 v38, v130, v133
	v_cvt_pk_bf16_f32 v39, v134, v137
	v_cvt_pk_bf16_f32 v40, v138, v141
	v_cvt_pk_bf16_f32 v41, v142, v144
	v_cvt_pk_bf16_f32 v42, v145, v146
	v_cvt_pk_bf16_f32 v43, v147, v148
	v_cvt_pk_bf16_f32 v44, v149, v150
	v_cvt_pk_bf16_f32 v45, v151, v152
	v_cvt_pk_bf16_f32 v46, v153, v154
	v_cvt_pk_bf16_f32 v47, v155, v156
	v_cvt_pk_bf16_f32 v48, v157, v158
	v_cvt_pk_bf16_f32 v49, v159, v160
	s_add_i32 s57, s72, 0
	v_add_u32_e32 v0, s57, v125
	ds_read_b64_tr_b16 v[130:131], v0 offset:8192
	ds_read_b64_tr_b16 v[132:133], v0 offset:8704
	ds_read_b64_tr_b16 v[134:135], v0 offset:12288
	v_max_f32_e32 v129, v67, v67
	s_waitcnt lgkmcnt(1)
	v_mfma_f32_32x32x16_bf16 v[18:33], v[130:133], v[34:37], v[18:33]
	ds_read_b64_tr_b16 v[136:137], v0 offset:12800
	ds_read_b64_tr_b16 v[130:131], v0 offset:9216
	s_waitcnt lgkmcnt(1)
	v_mfma_f32_32x32x16_bf16 v[2:17], v[134:137], v[34:37], v[2:17]
	ds_read_b64_tr_b16 v[132:133], v0 offset:9728
	ds_read_b64_tr_b16 v[34:35], v0 offset:13312
	s_waitcnt lgkmcnt(1)
	v_mfma_f32_32x32x16_bf16 v[18:33], v[130:133], v[38:41], v[18:33]
	ds_read_b64_tr_b16 v[36:37], v0 offset:13824
	ds_read_b64_tr_b16 v[130:131], v0 offset:10240
	s_waitcnt lgkmcnt(1)
	v_mfma_f32_32x32x16_bf16 v[2:17], v[34:37], v[38:41], v[2:17]
	ds_read_b64_tr_b16 v[132:133], v0 offset:10752
	ds_read_b64_tr_b16 v[34:35], v0 offset:11264
	ds_read_b64_tr_b16 v[36:37], v0 offset:11776
	ds_read_b64_tr_b16 v[38:39], v0 offset:14336
	ds_read_b64_tr_b16 v[40:41], v0 offset:14848
	ds_read_b64_tr_b16 v[134:135], v0 offset:15360
	ds_read_b64_tr_b16 v[136:137], v0 offset:15872
	s_waitcnt lgkmcnt(6)
	v_mfma_f32_32x32x16_bf16 v[18:33], v[130:133], v[42:45], v[18:33]
	v_max_f32_e32 v130, v83, v83
	v_max_f32_e32 v129, v130, v129
	v_max3_f32 v130, v82, v66, v84
	v_max3_f32 v129, v129, v85, v69
	v_max3_f32 v130, v130, v68, v86
	v_max3_f32 v129, v129, v87, v71
	s_waitcnt lgkmcnt(2)
	v_mfma_f32_32x32x16_bf16 v[2:17], v[38:41], v[42:45], v[2:17]
	v_max3_f32 v38, v130, v70, v88
	v_max3_f32 v39, v129, v89, v73
	v_max3_f32 v38, v38, v72, v90
	v_max3_f32 v39, v39, v91, v75
	v_max3_f32 v38, v38, v74, v92
	v_max3_f32 v39, v39, v93, v77
	v_max3_f32 v38, v38, v76, v94
	v_mfma_f32_32x32x16_bf16 v[18:33], v[34:37], v[46:49], v[18:33]
	v_max3_f32 v34, v39, v95, v79
	v_max3_f32 v35, v38, v78, v96
	v_max3_f32 v34, v34, v97, v81
	v_add_f32_e32 v36, v160, v161
	v_max3_f32 v34, v35, v80, v34
	v_add_f32_e32 v128, v128, v36
	v_cmp_lt_f32_e32 vcc, s33, v34
	s_waitcnt lgkmcnt(0)
	v_mfma_f32_32x32x16_bf16 v[2:17], v[134:137], v[46:49], v[2:17]
	s_cbranch_vccz .LBB0_401
	v_mov_b32_e32 v35, v34
	s_nop 1
	v_permlane32_swap_b32 v34, v35
	s_nop 1
	s_nop 0
	v_max3_f32 v36, v34, v35, 0
	v_exp_f32_e64 v38, -v36
	v_add_f32_e32 v127, v127, v36
	v_xor_b32_e32 v34, 0x80000000, v127
	v_pk_add_f32 v[82:83], v[82:83], v[36:37] op_sel_hi:[1,0] neg_lo:[0,1] neg_hi:[0,1]
	v_pk_add_f32 v[66:67], v[66:67], v[36:37] op_sel_hi:[1,0] neg_lo:[0,1] neg_hi:[0,1]
	v_pk_add_f32 v[84:85], v[84:85], v[36:37] op_sel_hi:[1,0] neg_lo:[0,1] neg_hi:[0,1]
	v_pk_add_f32 v[68:69], v[68:69], v[36:37] op_sel_hi:[1,0] neg_lo:[0,1] neg_hi:[0,1]
	v_pk_add_f32 v[86:87], v[86:87], v[36:37] op_sel_hi:[1,0] neg_lo:[0,1] neg_hi:[0,1]
	v_pk_add_f32 v[70:71], v[70:71], v[36:37] op_sel_hi:[1,0] neg_lo:[0,1] neg_hi:[0,1]
	v_pk_add_f32 v[88:89], v[88:89], v[36:37] op_sel_hi:[1,0] neg_lo:[0,1] neg_hi:[0,1]
	v_pk_add_f32 v[72:73], v[72:73], v[36:37] op_sel_hi:[1,0] neg_lo:[0,1] neg_hi:[0,1]
	v_pk_add_f32 v[90:91], v[90:91], v[36:37] op_sel_hi:[1,0] neg_lo:[0,1] neg_hi:[0,1]
	v_pk_add_f32 v[74:75], v[74:75], v[36:37] op_sel_hi:[1,0] neg_lo:[0,1] neg_hi:[0,1]
	v_pk_add_f32 v[92:93], v[92:93], v[36:37] op_sel_hi:[1,0] neg_lo:[0,1] neg_hi:[0,1]
	v_pk_add_f32 v[76:77], v[76:77], v[36:37] op_sel_hi:[1,0] neg_lo:[0,1] neg_hi:[0,1]
	v_pk_add_f32 v[94:95], v[94:95], v[36:37] op_sel_hi:[1,0] neg_lo:[0,1] neg_hi:[0,1]
	v_pk_add_f32 v[78:79], v[78:79], v[36:37] op_sel_hi:[1,0] neg_lo:[0,1] neg_hi:[0,1]
	v_pk_add_f32 v[96:97], v[96:97], v[36:37] op_sel_hi:[1,0] neg_lo:[0,1] neg_hi:[0,1]
	v_pk_add_f32 v[80:81], v[80:81], v[36:37] op_sel_hi:[1,0] neg_lo:[0,1] neg_hi:[0,1]
	v_pk_mul_f32 v[32:33], v[32:33], v[38:39] op_sel_hi:[1,0]
	v_pk_mul_f32 v[30:31], v[30:31], v[38:39] op_sel_hi:[1,0]
	v_pk_mul_f32 v[28:29], v[28:29], v[38:39] op_sel_hi:[1,0]
	v_pk_mul_f32 v[26:27], v[26:27], v[38:39] op_sel_hi:[1,0]
	v_pk_mul_f32 v[24:25], v[24:25], v[38:39] op_sel_hi:[1,0]
	v_pk_mul_f32 v[22:23], v[22:23], v[38:39] op_sel_hi:[1,0]
	v_pk_mul_f32 v[20:21], v[20:21], v[38:39] op_sel_hi:[1,0]
	v_pk_mul_f32 v[18:19], v[18:19], v[38:39] op_sel_hi:[1,0]
	v_pk_mul_f32 v[16:17], v[16:17], v[38:39] op_sel_hi:[1,0]
	v_pk_mul_f32 v[14:15], v[14:15], v[38:39] op_sel_hi:[1,0]
	v_pk_mul_f32 v[12:13], v[12:13], v[38:39] op_sel_hi:[1,0]
	v_pk_mul_f32 v[10:11], v[10:11], v[38:39] op_sel_hi:[1,0]
	v_pk_mul_f32 v[8:9], v[8:9], v[38:39] op_sel_hi:[1,0]
	v_pk_mul_f32 v[6:7], v[6:7], v[38:39] op_sel_hi:[1,0]
	v_pk_mul_f32 v[4:5], v[4:5], v[38:39] op_sel_hi:[1,0]
	v_pk_mul_f32 v[2:3], v[2:3], v[38:39] op_sel_hi:[1,0]
	v_mul_f32_e32 v128, v128, v38
	v_mov_b32_e32 v35, v34
	v_mov_b32_e32 v36, v34
	v_mov_b32_e32 v37, v34
	v_mov_b32_e32 v38, v34
	v_mov_b32_e32 v39, v34
	v_mov_b32_e32 v40, v34
	v_mov_b32_e32 v41, v34
	v_mov_b32_e32 v42, v34
	v_mov_b32_e32 v43, v34
	v_mov_b32_e32 v44, v34
	v_mov_b32_e32 v45, v34
	v_mov_b32_e32 v46, v34
	v_mov_b32_e32 v47, v34
	v_mov_b32_e32 v48, v34
	v_mov_b32_e32 v49, v34
	v_mov_b32_e32 v50, v34
	v_mov_b32_e32 v51, v34
	v_mov_b32_e32 v52, v34
	v_mov_b32_e32 v53, v34
	v_mov_b32_e32 v54, v34
	v_mov_b32_e32 v55, v34
	v_mov_b32_e32 v56, v34
	v_mov_b32_e32 v57, v34
	v_mov_b32_e32 v58, v34
	v_mov_b32_e32 v59, v34
	v_mov_b32_e32 v60, v34
	v_mov_b32_e32 v61, v34
	v_mov_b32_e32 v62, v34
	v_mov_b32_e32 v63, v34
	v_mov_b32_e32 v64, v34
	v_mov_b32_e32 v65, v34
	s_branch .LBB0_402

.LBB0_402:
	v_exp_f32_e32 v129, v82
	v_exp_f32_e32 v146, v83
	v_exp_f32_e32 v147, v84
	v_exp_f32_e32 v148, v85
	v_exp_f32_e32 v149, v86
	v_exp_f32_e32 v150, v87
	v_exp_f32_e32 v151, v88
	v_exp_f32_e32 v152, v89
	v_exp_f32_e32 v153, v90
	v_exp_f32_e32 v154, v91
	v_exp_f32_e32 v155, v92
	v_exp_f32_e32 v156, v93
	v_exp_f32_e32 v157, v94
	v_exp_f32_e32 v158, v95
	v_exp_f32_e32 v159, v96
	v_exp_f32_e32 v160, v97
	s_add_i32 s58, s55, 4
	s_and_b32 s59, s56, 0xf00000
	s_and_b32 s58, s58, 3
	s_lshl_b32 s78, s59, 1
	v_lshl_add_u64 v[82:83], v[116:117], 0, s[78:79]
	s_mul_i32 s58, s58, 0x38000
	s_mov_b32 s59, s79
	s_add_i32 s60, s57, s5
	v_lshl_add_u64 v[82:83], v[82:83], 0, s[58:59]
	s_mov_b32 m0, s60
	s_waitcnt vmcnt(0)
	s_barrier
	v_add_u32_e32 v142, s54, v126
	ds_read_b128 v[130:133], v142
	ds_read_b128 v[134:137], v142 offset:2048
	global_load_lds_dwordx4 v[82:83], off
	v_lshl_add_u64 v[82:83], v[118:119], 0, s[78:79]
	v_lshl_add_u64 v[82:83], v[82:83], 0, s[58:59]
	s_add_i32 m0, s60, 0x2000
	s_nop 0
	global_load_lds_dwordx4 v[82:83], off
	v_exp_f32_e32 v161, v66
	v_exp_f32_e32 v162, v67
	v_exp_f32_e32 v163, v68
	v_exp_f32_e32 v164, v69
	ds_read_b128 v[66:69], v142 offset:4096
	v_exp_f32_e32 v165, v70
	v_exp_f32_e32 v166, v71
	s_waitcnt lgkmcnt(0)
	v_mfma_f32_32x32x16_bf16 v[82:97], v[130:133], v[110:113], v[34:49]
	v_exp_f32_e32 v167, v72
	v_exp_f32_e32 v168, v73
	ds_read_b128 v[70:73], v142 offset:6144
	v_exp_f32_e32 v169, v74
	v_exp_f32_e32 v170, v75
	v_exp_f32_e32 v171, v76
	v_exp_f32_e32 v172, v77
	v_mfma_f32_32x32x16_bf16 v[82:97], v[134:137], v[106:109], v[82:97]
	ds_read_b128 v[130:133], v142 offset:512
	ds_read_b128 v[134:137], v142 offset:2560
	ds_read_b128 v[138:141], v142 offset:4608
	ds_read_b128 v[142:145], v142 offset:6656
	v_exp_f32_e32 v173, v78
	v_exp_f32_e32 v174, v79
	v_exp_f32_e32 v175, v80
	v_exp_f32_e32 v176, v81
	v_mfma_f32_32x32x16_bf16 v[82:97], v[66:69], v[102:105], v[82:97]
	v_add_f32_e32 v66, v129, v146
	v_add_f32_e32 v66, v147, v66
	v_add_f32_e32 v66, v148, v66
	v_add_f32_e32 v66, v149, v66
	v_add_f32_e32 v66, v150, v66
	v_add_f32_e32 v66, v151, v66
	v_add_f32_e32 v66, v152, v66
	v_add_f32_e32 v66, v153, v66
	s_waitcnt lgkmcnt(0)
	v_mfma_f32_32x32x16_bf16 v[82:97], v[70:73], v[98:101], v[82:97]
	v_add_f32_e32 v177, v154, v66
	v_mfma_f32_32x32x16_bf16 v[66:81], v[130:133], v[110:113], v[34:49]
	v_add_f32_e32 v130, v155, v177
	v_add_f32_e32 v130, v156, v130
	v_add_f32_e32 v130, v157, v130
	v_add_f32_e32 v130, v158, v130
	v_add_f32_e32 v130, v159, v130
	v_add_f32_e32 v130, v160, v130
	v_add_f32_e32 v130, v161, v130
	v_mfma_f32_32x32x16_bf16 v[66:81], v[134:137], v[106:109], v[66:81]
	v_add_f32_e32 v130, v162, v130
	v_add_f32_e32 v130, v163, v130
	v_add_f32_e32 v130, v164, v130
	v_add_f32_e32 v130, v165, v130
	v_add_f32_e32 v130, v166, v130
	v_add_f32_e32 v130, v167, v130
	v_add_f32_e32 v130, v168, v130
	v_mfma_f32_32x32x16_bf16 v[66:81], v[138:141], v[102:105], v[66:81]
	v_add_f32_e32 v130, v169, v130
	v_add_f32_e32 v130, v170, v130
	v_add_f32_e32 v130, v171, v130
	v_add_f32_e32 v130, v172, v130
	v_add_f32_e32 v130, v173, v130
	v_add_f32_e32 v130, v174, v130
	v_add_f32_e32 v177, v175, v130
	v_mfma_f32_32x32x16_bf16 v[66:81], v[142:145], v[98:101], v[66:81]
	v_cvt_pk_bf16_f32 v130, v129, v146
	v_cvt_pk_bf16_f32 v131, v147, v148
	v_cvt_pk_bf16_f32 v132, v149, v150
	v_cvt_pk_bf16_f32 v133, v151, v152
	v_cvt_pk_bf16_f32 v134, v153, v154
	v_cvt_pk_bf16_f32 v135, v155, v156
	v_cvt_pk_bf16_f32 v136, v157, v158
	v_cvt_pk_bf16_f32 v137, v159, v160
	v_cvt_pk_bf16_f32 v138, v161, v162
	v_cvt_pk_bf16_f32 v139, v163, v164
	v_cvt_pk_bf16_f32 v140, v165, v166
	v_cvt_pk_bf16_f32 v141, v167, v168
	v_cvt_pk_bf16_f32 v142, v169, v170
	v_cvt_pk_bf16_f32 v143, v171, v172
	v_cvt_pk_bf16_f32 v144, v173, v174
	v_cvt_pk_bf16_f32 v145, v175, v176
	v_add_u32_e32 v129, s53, v125
	ds_read_b64_tr_b16 v[146:147], v129 offset:8192
	ds_read_b64_tr_b16 v[148:149], v129 offset:8704
	ds_read_b64_tr_b16 v[150:151], v129 offset:12288
	s_waitcnt lgkmcnt(1)
	v_mfma_f32_32x32x16_bf16 v[18:33], v[146:149], v[130:133], v[18:33]
	ds_read_b64_tr_b16 v[152:153], v129 offset:12800
	ds_read_b64_tr_b16 v[146:147], v129 offset:9216
	s_waitcnt lgkmcnt(1)
	v_mfma_f32_32x32x16_bf16 v[2:17], v[150:153], v[130:133], v[2:17]
	ds_read_b64_tr_b16 v[148:149], v129 offset:9728
	ds_read_b64_tr_b16 v[130:131], v129 offset:13312
	s_waitcnt lgkmcnt(1)
	v_mfma_f32_32x32x16_bf16 v[18:33], v[146:149], v[134:137], v[18:33]
	ds_read_b64_tr_b16 v[132:133], v129 offset:13824
	ds_read_b64_tr_b16 v[146:147], v129 offset:10240
	s_waitcnt lgkmcnt(1)
	v_mfma_f32_32x32x16_bf16 v[2:17], v[130:133], v[134:137], v[2:17]
	ds_read_b64_tr_b16 v[148:149], v129 offset:10752
	ds_read_b64_tr_b16 v[130:131], v129 offset:11264
	ds_read_b64_tr_b16 v[132:133], v129 offset:11776
	ds_read_b64_tr_b16 v[134:135], v129 offset:14336
	ds_read_b64_tr_b16 v[136:137], v129 offset:14848
	ds_read_b64_tr_b16 v[150:151], v129 offset:15360
	ds_read_b64_tr_b16 v[152:153], v129 offset:15872
	v_max_f32_e32 v129, v67, v67
	s_waitcnt lgkmcnt(6)
	v_mfma_f32_32x32x16_bf16 v[18:33], v[146:149], v[138:141], v[18:33]
	v_max_f32_e32 v146, v83, v83
	v_max_f32_e32 v129, v146, v129
	v_max3_f32 v146, v82, v66, v84
	v_max3_f32 v129, v129, v85, v69
	v_max3_f32 v146, v146, v68, v86
	v_max3_f32 v129, v129, v87, v71
	v_max3_f32 v129, v129, v89, v73
	s_waitcnt lgkmcnt(2)
	v_mfma_f32_32x32x16_bf16 v[2:17], v[134:137], v[138:141], v[2:17]
	v_max3_f32 v134, v146, v70, v88
	v_max3_f32 v134, v134, v72, v90
	v_max3_f32 v129, v129, v91, v75
	v_max3_f32 v134, v134, v74, v92
	v_max3_f32 v129, v129, v93, v77
	v_max3_f32 v134, v134, v76, v94
	v_max3_f32 v129, v129, v95, v79
	v_mfma_f32_32x32x16_bf16 v[18:33], v[130:133], v[142:145], v[18:33]
	v_max3_f32 v130, v134, v78, v96
	v_max3_f32 v129, v129, v97, v81
	v_add_f32_e32 v131, v176, v177
	v_max3_f32 v129, v130, v80, v129
	v_add_f32_e32 v128, v128, v131
	v_cmp_lt_f32_e32 vcc, s33, v129
	s_waitcnt lgkmcnt(0)
	v_mfma_f32_32x32x16_bf16 v[2:17], v[150:153], v[142:145], v[2:17]
	s_cbranch_vccz .LBB0_404
	v_mov_b32_e32 v34, v129
	s_nop 1
	v_permlane32_swap_b32 v129, v34
	s_nop 1
	s_nop 0
	v_max3_f32 v36, v129, v34, 0
	v_exp_f32_e64 v38, -v36
	v_add_f32_e32 v127, v127, v36
	v_xor_b32_e32 v34, 0x80000000, v127
	v_pk_add_f32 v[82:83], v[82:83], v[36:37] op_sel_hi:[1,0] neg_lo:[0,1] neg_hi:[0,1]
	v_pk_add_f32 v[84:85], v[84:85], v[36:37] op_sel_hi:[1,0] neg_lo:[0,1] neg_hi:[0,1]
	v_pk_add_f32 v[86:87], v[86:87], v[36:37] op_sel_hi:[1,0] neg_lo:[0,1] neg_hi:[0,1]
	v_pk_add_f32 v[88:89], v[88:89], v[36:37] op_sel_hi:[1,0] neg_lo:[0,1] neg_hi:[0,1]
	v_pk_add_f32 v[90:91], v[90:91], v[36:37] op_sel_hi:[1,0] neg_lo:[0,1] neg_hi:[0,1]
	v_pk_add_f32 v[92:93], v[92:93], v[36:37] op_sel_hi:[1,0] neg_lo:[0,1] neg_hi:[0,1]
	v_pk_add_f32 v[94:95], v[94:95], v[36:37] op_sel_hi:[1,0] neg_lo:[0,1] neg_hi:[0,1]
	v_pk_add_f32 v[96:97], v[96:97], v[36:37] op_sel_hi:[1,0] neg_lo:[0,1] neg_hi:[0,1]
	v_sub_f32_e32 v81, v81, v36
	v_sub_f32_e32 v80, v80, v36
	v_sub_f32_e32 v79, v79, v36
	v_sub_f32_e32 v78, v78, v36
	v_sub_f32_e32 v77, v77, v36
	v_sub_f32_e32 v76, v76, v36
	v_sub_f32_e32 v75, v75, v36
	v_sub_f32_e32 v74, v74, v36
	v_sub_f32_e32 v73, v73, v36
	v_sub_f32_e32 v72, v72, v36
	v_sub_f32_e32 v71, v71, v36
	v_sub_f32_e32 v70, v70, v36
	v_sub_f32_e32 v69, v69, v36
	v_sub_f32_e32 v68, v68, v36
	v_sub_f32_e32 v67, v67, v36
	v_sub_f32_e32 v66, v66, v36
	v_pk_mul_f32 v[32:33], v[32:33], v[38:39] op_sel_hi:[1,0]
	v_pk_mul_f32 v[30:31], v[30:31], v[38:39] op_sel_hi:[1,0]
	v_pk_mul_f32 v[28:29], v[28:29], v[38:39] op_sel_hi:[1,0]
	v_pk_mul_f32 v[26:27], v[26:27], v[38:39] op_sel_hi:[1,0]
	v_pk_mul_f32 v[24:25], v[24:25], v[38:39] op_sel_hi:[1,0]
	v_pk_mul_f32 v[22:23], v[22:23], v[38:39] op_sel_hi:[1,0]
	v_pk_mul_f32 v[20:21], v[20:21], v[38:39] op_sel_hi:[1,0]
	v_pk_mul_f32 v[18:19], v[18:19], v[38:39] op_sel_hi:[1,0]
	v_pk_mul_f32 v[16:17], v[16:17], v[38:39] op_sel_hi:[1,0]
	v_pk_mul_f32 v[14:15], v[14:15], v[38:39] op_sel_hi:[1,0]
	v_pk_mul_f32 v[12:13], v[12:13], v[38:39] op_sel_hi:[1,0]
	v_pk_mul_f32 v[10:11], v[10:11], v[38:39] op_sel_hi:[1,0]
	v_pk_mul_f32 v[8:9], v[8:9], v[38:39] op_sel_hi:[1,0]
	v_pk_mul_f32 v[6:7], v[6:7], v[38:39] op_sel_hi:[1,0]
	v_pk_mul_f32 v[4:5], v[4:5], v[38:39] op_sel_hi:[1,0]
	v_pk_mul_f32 v[2:3], v[2:3], v[38:39] op_sel_hi:[1,0]
	v_mul_f32_e32 v128, v128, v38
	v_mov_b32_e32 v35, v34
	v_mov_b32_e32 v36, v34
	v_mov_b32_e32 v37, v34
	v_mov_b32_e32 v38, v34
	v_mov_b32_e32 v39, v34
	v_mov_b32_e32 v40, v34
	v_mov_b32_e32 v41, v34
	v_mov_b32_e32 v42, v34
	v_mov_b32_e32 v43, v34
	v_mov_b32_e32 v44, v34
	v_mov_b32_e32 v45, v34
	v_mov_b32_e32 v46, v34
	v_mov_b32_e32 v47, v34
	v_mov_b32_e32 v48, v34
	v_mov_b32_e32 v49, v34
	v_mov_b32_e32 v50, v34
	v_mov_b32_e32 v51, v34
	v_mov_b32_e32 v52, v34
	v_mov_b32_e32 v53, v34
	v_mov_b32_e32 v54, v34
	v_mov_b32_e32 v55, v34
	v_mov_b32_e32 v56, v34
	v_mov_b32_e32 v57, v34
	v_mov_b32_e32 v58, v34
	v_mov_b32_e32 v59, v34
	v_mov_b32_e32 v60, v34
	v_mov_b32_e32 v61, v34
	v_mov_b32_e32 v62, v34
	v_mov_b32_e32 v63, v34
	v_mov_b32_e32 v64, v34
	v_mov_b32_e32 v65, v34

	.amdhsa_kernel _Z10fwd_kernel4Args
		.amdhsa_group_segment_fixed_size 0
		.amdhsa_private_segment_fixed_size 0
		.amdhsa_kernarg_size 400
		.amdhsa_user_sgpr_count 2
		.amdhsa_user_sgpr_dispatch_ptr 0
		.amdhsa_user_sgpr_queue_ptr 0
		.amdhsa_user_sgpr_kernarg_segment_ptr 1
		.amdhsa_user_sgpr_dispatch_id 0
		.amdhsa_user_sgpr_kernarg_preload_length 0
		.amdhsa_user_sgpr_kernarg_preload_offset 0
		.amdhsa_user_sgpr_private_segment_size 0
		.amdhsa_uses_dynamic_stack 0
		.amdhsa_enable_private_segment 0
		.amdhsa_system_sgpr_workgroup_id_x 1
		.amdhsa_system_sgpr_workgroup_id_y 0
		.amdhsa_system_sgpr_workgroup_id_z 0
		.amdhsa_system_sgpr_workgroup_info 0
		.amdhsa_system_vgpr_workitem_id 2
		.amdhsa_next_free_vgpr 240
		.amdhsa_next_free_sgpr 98
		.amdhsa_accum_offset 240
		.amdhsa_reserve_vcc 1
		.amdhsa_float_round_mode_32 0
		.amdhsa_float_round_mode_16_64 0
		.amdhsa_float_denorm_mode_32 3
		.amdhsa_float_denorm_mode_16_64 3
		.amdhsa_dx10_clamp 1
		.amdhsa_ieee_mode 1
		.amdhsa_fp16_overflow 0
		.amdhsa_tg_split 0
		.amdhsa_exception_fp_ieee_invalid_op 0
		.amdhsa_exception_fp_denorm_src 0
		.amdhsa_exception_fp_ieee_div_zero 0
		.amdhsa_exception_fp_ieee_overflow 0
		.amdhsa_exception_fp_ieee_underflow 0
		.amdhsa_exception_fp_ieee_inexact 0
		.amdhsa_exception_int_div_zero 0
	.end_amdhsa_kernel

amdhsa.kernels:
  - .agpr_count:     0
    .args:
      - .offset:         0
        .size:           144
        .value_kind:     by_value
      - .offset:         144
        .size:           4
        .value_kind:     hidden_block_count_x
      - .offset:         148
        .size:           4
        .value_kind:     hidden_block_count_y
      - .offset:         152
        .size:           4
        .value_kind:     hidden_block_count_z
      - .offset:         156
        .size:           2
        .value_kind:     hidden_group_size_x
      - .offset:         158
        .size:           2
        .value_kind:     hidden_group_size_y
      - .offset:         160
        .size:           2
        .value_kind:     hidden_group_size_z
      - .offset:         162
        .size:           2
        .value_kind:     hidden_remainder_x
      - .offset:         164
        .size:           2
        .value_kind:     hidden_remainder_y
      - .offset:         166
        .size:           2
        .value_kind:     hidden_remainder_z
      - .offset:         184
        .size:           8
        .value_kind:     hidden_global_offset_x
      - .offset:         192
        .size:           8
        .value_kind:     hidden_global_offset_y
      - .offset:         200
        .size:           8
        .value_kind:     hidden_global_offset_z
      - .offset:         208
        .size:           2
        .value_kind:     hidden_grid_dims
      - .offset:         232
        .size:           8
        .value_kind:     hidden_multigrid_sync_arg
      - .offset:         264
        .size:           4
        .value_kind:     hidden_dynamic_lds_size
    .group_segment_fixed_size: 0
    .kernarg_segment_align: 8
    .kernarg_segment_size: 400
    .language:       OpenCL C
    .language_version:
      - 2
      - 0
    .max_flat_workgroup_size: 512
    .name:           _Z10fwd_kernel4Args
    .private_segment_fixed_size: 0
    .sgpr_count:     104
    .sgpr_spill_count: 216
    .symbol:         _Z10fwd_kernel4Args.kd
    .uniform_work_group_size: 1
    .uses_dynamic_stack: false
    .vgpr_count:     240
    .vgpr_spill_count: 0
    .wavefront_size: 64
